# P5 rows processed in descending order (freshest delta rows first)
# speedup vs baseline: 1.0061x; 1.0061x over previous
; __device__ __forceinline__ float bf_lo(unsigned w) { return __uint_as_float(w << 16); }
; __device__ __forceinline__ float bf_hi(unsigned w) { return __uint_as_float(w & 0xffff0000u); }
; template <int NR>
; __device__ __forceinline__ void p5_rows(const Params& p, const bf16_t* __restrict__ DL, int r, int nw, int lane) {
;     f32x4 v[NR][8]; u32x4 d[NR][4];
; #pragma unroll
;     for (int k = 0; k < NR; ++k) { const int row = r + k * nw; const float* x = row < TP ? p.xp + (size_t)row * D : p.xs + (size_t)(row - TP) * D;
; #pragma unroll
;         for (int i = 0; i < 4; ++i) { v[k][2 * i] = *(const f32x4*)(x + (i * 64 + lane) * 8); v[k][2 * i + 1] = *(const f32x4*)(x + (i * 64 + lane) * 8 + 4);
;             d[k][i] = *(const u32x4*)(DL + (size_t)row * LDP + (i * 64 + lane) * 8); } }
; #pragma unroll
;     for (int k = 0; k < NR; ++k) { const int row = r + k * nw; float ss = 0.f;
; #pragma unroll
;         for (int i = 0; i < 4; ++i) { const u32x4 w = d[k][i];
;             v[k][2 * i] += (f32x4){bf_lo(w.x), bf_hi(w.x), bf_lo(w.y), bf_hi(w.y)}; v[k][2 * i + 1] += (f32x4){bf_lo(w.z), bf_hi(w.z), bf_lo(w.w), bf_hi(w.w)}; }
; __device__ __forceinline__ void phase5(const Params& p) {
;     int t_ = threadIdx.x; asm volatile("" : "+v"(t_));
;     const int lane = t_ & 63, gw = blockIdx.x * 8 + (t_ >> 6), nw = gridDim.x * 8;
;     const bf16_t* DL = (const bf16_t*)(p.ws + WS_H);
;     int r = gw;
;     for (; r + nw < T; r += 2 * nw) p5_rows<2>(p, DL, r, nw, lane);
;     if (r < T) p5_rows<1>(p, DL, r, nw, lane);
.LBB0_1188:
	s_or_b64 exec, exec, s[2:3]
	s_waitcnt lgkmcnt(0)
	s_barrier
	s_mov_b32 s0, 0x8800
	v_ashrrev_i32_e32 v95, 6, v0
	s_mul_i32 s1, s74, 15
	s_nop 0
	v_add_u32_e32 v95, s1, v95
	v_add_u32_e32 v70, s30, v95
	v_and_b32_e32 v1, 63, v0
	v_add_u32_e32 v6, s74, v70
	v_cmp_gt_i32_e32 vcc, s0, v6
	v_lshlrev_b32_e32 v68, 5, v1
	v_lshlrev_b32_e32 v72, 4, v1
	s_and_saveexec_b64 s[0:1], vcc
	s_cbranch_execz .LBB0_1198
	v_lshlrev_b32_e32 v0, 3, v1
	v_mbcnt_hi_u32_b32 v1, -1, v190
	v_and_b32_e32 v3, 64, v1
	v_add_u32_e32 v3, 64, v3
	v_xor_b32_e32 v5, 32, v1
	v_cmp_lt_i32_e32 vcc, v5, v3
	v_or_b32_e32 v2, 0x400, v0
	v_mov_b32_e32 v75, 0
	v_cndmask_b32_e32 v5, v1, v5, vcc
	v_lshlrev_b32_e32 v100, 2, v5
	v_xor_b32_e32 v5, 16, v1
	v_cmp_lt_i32_e32 vcc, v5, v3
	v_or_b32_e32 v4, 0x600, v0
	s_lshl_b32 s2, s33, 4
	s_sub_i32 s2, 0, s2
	v_cndmask_b32_e32 v5, v1, v5, vcc
	v_lshlrev_b32_e32 v101, 2, v5
	v_xor_b32_e32 v5, 8, v1
	v_cmp_lt_i32_e32 vcc, v5, v3
	v_lshlrev_b32_e32 v74, 2, v2
	v_ashrrev_i32_e32 v71, 31, v70
	v_cndmask_b32_e32 v5, v1, v5, vcc
	v_lshlrev_b32_e32 v102, 2, v5
	v_xor_b32_e32 v5, 4, v1
	v_cmp_lt_i32_e32 vcc, v5, v3
	v_mov_b32_e32 v69, v75
	v_lshl_add_u64 v[78:79], s[22:23], 0, v[74:75]
	v_cndmask_b32_e32 v5, v1, v5, vcc
	v_lshlrev_b32_e32 v103, 2, v5
	v_xor_b32_e32 v5, 2, v1
	v_cmp_lt_i32_e32 vcc, v5, v3
	v_lshlrev_b32_e32 v74, 2, v4
	v_mov_b32_e32 v73, v75
	v_cndmask_b32_e32 v5, v1, v5, vcc
	v_lshlrev_b32_e32 v104, 2, v5
	v_xor_b32_e32 v5, 1, v1
	v_cmp_lt_i32_e32 vcc, v5, v3
	s_ashr_i32 s3, s2, 31
	v_lshlrev_b64 v[8:9], 13, v[70:71]
	v_cndmask_b32_e32 v1, v1, v5, vcc
	v_lshlrev_b32_e32 v86, 2, v2
	v_lshlrev_b32_e32 v88, 2, v4
	v_lshlrev_b32_e32 v105, 2, v1
	v_lshl_add_u64 v[76:77], s[22:23], 0, v[68:69]
	v_lshl_add_u64 v[80:81], s[22:23], 0, v[74:75]
	v_lshl_add_u64 v[82:83], s[26:27], 0, v[72:73]
	v_lshl_add_u64 v[84:85], s[36:37], 0, v[8:9]
	s_lshl_b64 s[4:5], s[2:3], 13
	s_add_i32 s9, s74, s30
	s_mov_b64 s[6:7], 0
	s_movk_i32 s12, 0x7fff
	s_movk_i32 s13, 0x1080
	s_mov_b32 s8, 0x3a000000
	s_mov_b32 s14, 0x800000
	s_mov_b32 s15, 0x87ff
	v_lshlrev_b32_e32 v74, 2, v0
	v_mov_b32_e32 v90, v86
	v_mov_b32_e32 v91, v75
	v_mov_b32_e32 v92, v88
	v_mov_b32_e32 v93, v75
	v_mov_b32_e32 v94, 0x358637bd
	s_branch .LBB0_1191
.LBB0_1190:
	s_or_b64 exec, exec, s[10:11]
	v_mad_u64_u32 v[4:5], s[10:11], v6, s13, v[82:83]
	v_mov_b32_e32 v6, v5
	v_lshl_add_u64 v[2:3], v[0:1], 0, v[74:75]
	v_mad_u64_u32 v[6:7], s[10:11], v7, s13, v[6:7]
	global_load_dwordx4 v[106:109], v[2:3], off offset:16
	global_load_dwordx4 v[110:113], v[2:3], off
	v_mov_b32_e32 v5, v6
	global_load_dwordx4 v[114:117], v[2:3], off offset:2064
	global_load_dwordx4 v[118:121], v[2:3], off offset:2048
	global_load_dwordx4 v[122:125], v[4:5], off
	global_load_dwordx4 v[126:129], v[4:5], off offset:1024
	v_mov_b32_e32 v87, v75
	v_mov_b32_e32 v89, v75
	v_lshl_add_u64 v[2:3], v[0:1], 0, v[86:87]
	v_lshl_add_u64 v[6:7], v[0:1], 0, v[88:89]
	global_load_dwordx4 v[12:15], v[2:3], off offset:16
	global_load_dwordx4 v[16:19], v[2:3], off
	s_nop 0
	global_load_dwordx4 v[0:3], v[6:7], off offset:16
	global_load_dwordx4 v[8:11], v[6:7], off
	global_load_dwordx4 v[130:133], v[4:5], off offset:2048
	s_nop 0
	global_load_dwordx4 v[4:7], v[4:5], off offset:3072
	s_waitcnt vmcnt(19)
	v_lshlrev_b32_e32 v134, 16, v64
	v_and_b32_e32 v135, 0xffff0000, v64
	v_lshlrev_b32_e32 v64, 16, v65
	v_and_b32_e32 v65, 0xffff0000, v65
	v_pk_add_f32 v[62:63], v[62:63], v[64:65]
	v_lshlrev_b32_e32 v64, 16, v66
	v_and_b32_e32 v65, 0xffff0000, v66
	v_lshlrev_b32_e32 v66, 16, v67
	v_and_b32_e32 v67, 0xffff0000, v67
	v_pk_add_f32 v[58:59], v[58:59], v[66:67]
	v_pk_add_f32 v[56:57], v[56:57], v[64:65]
	s_waitcnt vmcnt(18)
	v_lshlrev_b32_e32 v64, 16, v48
	v_and_b32_e32 v65, 0xffff0000, v48
	v_lshlrev_b32_e32 v66, 16, v49
	v_and_b32_e32 v67, 0xffff0000, v49
	v_pk_add_f32 v[48:49], v[52:53], v[64:65]
	v_pk_add_f32 v[52:53], v[54:55], v[66:67]
	v_lshlrev_b32_e32 v54, 16, v50
	v_and_b32_e32 v55, 0xffff0000, v50
	v_lshlrev_b32_e32 v50, 16, v51
	v_and_b32_e32 v51, 0xffff0000, v51
	v_pk_add_f32 v[46:47], v[46:47], v[50:51]
	s_waitcnt vmcnt(13)
	v_lshlrev_b32_e32 v50, 16, v40
	v_and_b32_e32 v51, 0xffff0000, v40
	v_lshlrev_b32_e32 v40, 16, v41
	v_and_b32_e32 v41, 0xffff0000, v41
	v_pk_add_f32 v[38:39], v[38:39], v[40:41]
	v_lshlrev_b32_e32 v40, 16, v42
	v_and_b32_e32 v41, 0xffff0000, v42
	v_pk_add_f32 v[32:33], v[32:33], v[40:41]
	s_waitcnt vmcnt(12)
; __device__ __forceinline__ float bf_lo(unsigned w) { return __uint_as_float(w << 16); }
; __device__ __forceinline__ float bf_hi(unsigned w) { return __uint_as_float(w & 0xffff0000u); }
; template <int NR>
; __device__ __forceinline__ void p5_rows(const Params& p, const bf16_t* __restrict__ DL, int r, int nw, int lane) {
;     ...
;     for (int k = 0; k < NR; ++k) { const int row = r + k * nw; float ss = 0.f;
; #pragma unroll
;         for (int i = 0; i < 4; ++i) { const u32x4 w = d[k][i];
;             v[k][2 * i] += (f32x4){bf_lo(w.x), bf_hi(w.x), bf_lo(w.y), bf_hi(w.y)}; v[k][2 * i + 1] += (f32x4){bf_lo(w.z), bf_hi(w.z), bf_lo(w.w), bf_hi(w.w)}; }
; #pragma unroll
;         for (int i = 0; i < 8; ++i) ss += (v[k][i][0] * v[k][i][0] + v[k][i][1] * v[k][i][1]) + (v[k][i][2] * v[k][i][2] + v[k][i][3] * v[k][i][3]);
	v_lshlrev_b32_e32 v40, 16, v24
	v_and_b32_e32 v41, 0xffff0000, v24
	v_lshlrev_b32_e32 v24, 16, v25
	v_and_b32_e32 v25, 0xffff0000, v25
	v_pk_add_f32 v[60:61], v[60:61], v[134:135]
	v_pk_add_f32 v[24:25], v[30:31], v[24:25]
	v_lshlrev_b32_e32 v30, 16, v26
	v_and_b32_e32 v31, 0xffff0000, v26
	v_lshlrev_b32_e32 v26, 16, v27
	v_and_b32_e32 v27, 0xffff0000, v27
	v_pk_add_f32 v[20:21], v[20:21], v[30:31]
	v_mov_b32_e32 v30, v61
	v_mov_b32_e32 v31, v57
	v_pk_add_f32 v[28:29], v[28:29], v[40:41]
	v_pk_add_f32 v[22:23], v[22:23], v[26:27]
	v_mov_b32_e32 v26, v60
	v_mov_b32_e32 v27, v56
	v_pk_mul_f32 v[30:31], v[30:31], v[30:31]
	v_mov_b32_e32 v40, v63
	v_mov_b32_e32 v41, v59
	v_pk_fma_f32 v[26:27], v[26:27], v[26:27], v[30:31]
	v_mov_b32_e32 v30, v62
	v_mov_b32_e32 v31, v58
	v_pk_mul_f32 v[40:41], v[40:41], v[40:41]
	v_lshlrev_b32_e32 v42, 16, v43
	v_pk_fma_f32 v[30:31], v[30:31], v[30:31], v[40:41]
	v_and_b32_e32 v43, 0xffff0000, v43
	v_pk_add_f32 v[26:27], v[26:27], v[30:31]
	v_pk_mul_f32 v[30:31], v[52:53], v[52:53]
	v_pk_mul_f32 v[40:41], v[48:49], v[48:49]
	v_pk_add_f32 v[44:45], v[44:45], v[54:55]
	v_pk_add_f32 v[34:35], v[34:35], v[42:43]
	v_pk_mov_b32 v[42:43], v[40:41], v[30:31] op_sel:[1,0]
	v_mov_b32_e32 v41, v31
	v_pk_add_f32 v[36:37], v[36:37], v[50:51]
	v_pk_add_f32 v[30:31], v[42:43], v[40:41]
	v_mul_f32_e32 v40, v45, v45
	v_mul_f32_e32 v42, v36, v36
	v_pk_fma_f32 v[40:41], v[44:45], v[44:45], v[40:41] op_sel_hi:[1,1,0]
	v_mul_f32_e32 v50, v37, v37
	v_mov_b32_e32 v41, v42
	v_mul_f32_e32 v42, v47, v47
	v_mul_f32_e32 v51, v38, v38
	v_mul_f32_e32 v54, v39, v39
	v_pk_fma_f32 v[42:43], v[46:47], v[46:47], v[42:43] op_sel_hi:[1,1,0]
	v_pk_add_f32 v[26:27], v[26:27], v[26:27] op_sel:[0,1] op_sel_hi:[1,0]
	v_pk_add_f32 v[30:31], v[30:31], v[30:31] op_sel:[0,1] op_sel_hi:[1,0]
	v_mov_b32_e32 v43, v50
	v_mov_b32_e32 v27, v51
	v_mov_b32_e32 v31, v54
	v_pk_add_f32 v[40:41], v[40:41], v[42:43]
	v_pk_add_f32 v[26:27], v[26:27], v[30:31]
	global_load_dwordx4 v[134:137], v[76:77], off offset:16
	global_load_dwordx4 v[138:141], v[76:77], off
	v_pk_add_f32 v[26:27], v[40:41], v[26:27]
	v_pk_mul_f32 v[30:31], v[34:35], v[34:35]
	v_pk_add_f32 v[26:27], v[26:27], v[26:27] op_sel_hi:[0,1]
	v_pk_mul_f32 v[40:41], v[32:33], v[32:33]
	v_mul_f32_e32 v26, v28, v28
	v_pk_mov_b32 v[42:43], v[40:41], v[30:31] op_sel:[1,0]
	v_mov_b32_e32 v41, v31
	v_pk_add_f32 v[30:31], v[42:43], v[40:41]
	v_pk_fma_f32 v[40:41], v[28:29], v[28:29], v[26:27] op_sel_hi:[1,1,0]
	v_mul_f32_e32 v26, v24, v24
	v_pk_add_f32 v[30:31], v[30:31], v[30:31] op_sel_hi:[0,1]
	v_pk_fma_f32 v[42:43], v[24:25], v[24:25], v[26:27] op_sel_hi:[1,1,0]
	v_mul_f32_e32 v30, v20, v20
	v_mul_f32_e32 v26, v21, v21
	v_mul_f32_e32 v40, v22, v22
	v_mul_f32_e32 v42, v23, v23
	v_pk_add_f32 v[26:27], v[30:31], v[26:27]
	v_pk_add_f32 v[30:31], v[40:41], v[42:43]
	s_waitcnt vmcnt(9)
	v_lshlrev_b32_e32 v40, 16, v125
	v_pk_add_f32 v[142:143], v[26:27], v[30:31]
	v_lshlrev_b32_e32 v26, 16, v122
	v_and_b32_e32 v27, 0xffff0000, v122
	v_pk_add_f32 v[42:43], v[110:111], v[26:27]
	v_lshlrev_b32_e32 v26, 16, v124
	v_and_b32_e32 v27, 0xffff0000, v124
	v_pk_add_f32 v[66:67], v[106:107], v[26:27]
	s_waitcnt vmcnt(3)
	v_lshlrev_b32_e32 v106, 16, v130
	v_and_b32_e32 v107, 0xffff0000, v130
	v_pk_add_f32 v[16:17], v[16:17], v[106:107]
	v_lshlrev_b32_e32 v106, 16, v132
	v_and_b32_e32 v107, 0xffff0000, v132
	v_pk_add_f32 v[12:13], v[12:13], v[106:107]
	s_waitcnt vmcnt(2)
	v_lshlrev_b32_e32 v106, 16, v4
	v_and_b32_e32 v107, 0xffff0000, v4
	v_lshlrev_b32_e32 v4, 16, v5
	v_and_b32_e32 v5, 0xffff0000, v5
	v_lshlrev_b32_e32 v30, 16, v123
	v_and_b32_e32 v31, 0xffff0000, v123
	v_and_b32_e32 v41, 0xffff0000, v125
	v_pk_add_f32 v[4:5], v[10:11], v[4:5]
	v_lshlrev_b32_e32 v10, 16, v6
	v_and_b32_e32 v11, 0xffff0000, v6
	v_pk_add_f32 v[30:31], v[112:113], v[30:31]
	v_pk_add_f32 v[64:65], v[108:109], v[40:41]
	v_lshlrev_b32_e32 v6, 16, v7
	v_and_b32_e32 v7, 0xffff0000, v7
	v_pk_add_f32 v[0:1], v[0:1], v[10:11]
	v_mov_b32_e32 v10, v43
	v_mov_b32_e32 v11, v67
	v_pk_add_f32 v[8:9], v[8:9], v[106:107]
	v_pk_add_f32 v[2:3], v[2:3], v[6:7]
	v_mov_b32_e32 v6, v42
	v_mov_b32_e32 v7, v66
	v_pk_mul_f32 v[10:11], v[10:11], v[10:11]
	v_mov_b32_e32 v106, v31
	v_mov_b32_e32 v107, v65
	v_lshlrev_b32_e32 v26, 16, v126
	v_and_b32_e32 v27, 0xffff0000, v126
	v_lshlrev_b32_e32 v40, 16, v127
	v_and_b32_e32 v41, 0xffff0000, v127
	v_pk_fma_f32 v[6:7], v[6:7], v[6:7], v[10:11]
	v_mov_b32_e32 v10, v30
	v_mov_b32_e32 v11, v64
	v_pk_mul_f32 v[106:107], v[106:107], v[106:107]
	v_pk_add_f32 v[26:27], v[118:119], v[26:27]
	v_pk_add_f32 v[50:51], v[120:121], v[40:41]
	v_lshlrev_b32_e32 v108, 16, v131
	v_and_b32_e32 v109, 0xffff0000, v131
	v_pk_fma_f32 v[10:11], v[10:11], v[10:11], v[106:107]
	v_lshlrev_b32_e32 v54, 16, v128
	v_and_b32_e32 v55, 0xffff0000, v128
	v_lshlrev_b32_e32 v40, 16, v129
	v_and_b32_e32 v41, 0xffff0000, v129
	v_pk_add_f32 v[18:19], v[18:19], v[108:109]
	v_lshlrev_b32_e32 v108, 16, v133
	v_and_b32_e32 v109, 0xffff0000, v133
	v_pk_add_f32 v[6:7], v[6:7], v[10:11]
	v_pk_mul_f32 v[10:11], v[50:51], v[50:51]
	v_pk_mul_f32 v[106:107], v[26:27], v[26:27]
	v_pk_add_f32 v[40:41], v[116:117], v[40:41]
	v_pk_add_f32 v[54:55], v[114:115], v[54:55]
	v_pk_add_f32 v[14:15], v[14:15], v[108:109]
	v_pk_mov_b32 v[108:109], v[106:107], v[10:11] op_sel:[1,0]
	v_mov_b32_e32 v107, v11
	v_pk_add_f32 v[10:11], v[108:109], v[106:107]
	v_mul_f32_e32 v106, v55, v55
	v_mul_f32_e32 v108, v41, v41
	v_mul_f32_e32 v69, v16, v16
	v_mul_f32_e32 v73, v17, v17
	v_mul_f32_e32 v110, v18, v18
	v_mul_f32_e32 v111, v19, v19
	v_pk_fma_f32 v[106:107], v[54:55], v[54:55], v[106:107] op_sel_hi:[1,1,0]
; template <int NR>
; __device__ __forceinline__ void p5_rows(const Params& p, const bf16_t* __restrict__ DL, int r, int nw, int lane) {
;     ...
;         for (int i = 0; i < 8; ++i) ss += (v[k][i][0] * v[k][i][0] + v[k][i][1] * v[k][i][1]) + (v[k][i][2] * v[k][i][2] + v[k][i][3] * v[k][i][3]);
; #pragma unroll
;         for (int o = 32; o >= 1; o >>= 1) ss += __shfl_xor(ss, o);
;         const float rs = rsqrtf(ss * (1.0f / D) + EPS);
;         float* y = p.out + O_Y + (size_t)row * D;
; #pragma unroll
;         for (int i = 0; i < 4; ++i) { const f32x4 g0 = *(const f32x4*)(p.fng + (i * 64 + lane) * 8), g1 = *(const f32x4*)(p.fng + (i * 64 + lane) * 8 + 4);
;             *(f32x4*)(y + (i * 64 + lane) * 8) = v[k][2 * i] * rs * g0; *(f32x4*)(y + (i * 64 + lane) * 8 + 4) = v[k][2 * i + 1] * rs * g1; } }
	v_pk_fma_f32 v[108:109], v[40:41], v[40:41], v[108:109] op_sel_hi:[1,1,0]
	v_pk_add_f32 v[6:7], v[6:7], v[6:7] op_sel:[0,1] op_sel_hi:[1,0]
	v_pk_add_f32 v[10:11], v[10:11], v[10:11] op_sel:[0,1] op_sel_hi:[1,0]
	v_mov_b32_e32 v107, v69
	v_mov_b32_e32 v109, v73
	v_mov_b32_e32 v7, v110
	v_mov_b32_e32 v11, v111
	v_pk_add_f32 v[106:107], v[106:107], v[108:109]
	v_pk_add_f32 v[6:7], v[6:7], v[10:11]
	v_pk_mul_f32 v[10:11], v[14:15], v[14:15]
	v_pk_add_f32 v[6:7], v[106:107], v[6:7]
	v_pk_mul_f32 v[106:107], v[12:13], v[12:13]
	v_pk_add_f32 v[6:7], v[6:7], v[6:7] op_sel_hi:[0,1]
	v_pk_mov_b32 v[108:109], v[106:107], v[10:11] op_sel:[1,0]
	v_mov_b32_e32 v107, v11
	v_mul_f32_e32 v6, v8, v8
	v_pk_add_f32 v[10:11], v[108:109], v[106:107]
	v_pk_fma_f32 v[106:107], v[8:9], v[8:9], v[6:7] op_sel_hi:[1,1,0]
	v_mul_f32_e32 v6, v4, v4
	v_pk_add_f32 v[10:11], v[10:11], v[10:11] op_sel_hi:[0,1]
	v_pk_fma_f32 v[108:109], v[4:5], v[4:5], v[6:7] op_sel_hi:[1,1,0]
	v_mul_f32_e32 v10, v0, v0
	v_mul_f32_e32 v6, v1, v1
	v_mul_f32_e32 v106, v2, v2
	v_mul_f32_e32 v108, v3, v3
	v_pk_add_f32 v[6:7], v[10:11], v[6:7]
	v_pk_add_f32 v[10:11], v[106:107], v[108:109]
	v_lshl_add_u64 v[70:71], v[70:71], 0, s[2:3]
	v_pk_add_f32 v[6:7], v[6:7], v[10:11]
	v_mov_b32_e32 v11, v142
	v_mov_b32_e32 v10, v6
	v_mov_b32_e32 v142, v7
	v_pk_add_f32 v[6:7], v[10:11], v[142:143]
	ds_bpermute_b32 v11, v100, v7
	ds_bpermute_b32 v10, v100, v6
	v_lshl_add_u64 v[84:85], v[84:85], 0, s[4:5]
	s_waitcnt lgkmcnt(0)
	v_pk_add_f32 v[6:7], v[6:7], v[10:11]
	ds_bpermute_b32 v11, v101, v7
	ds_bpermute_b32 v10, v101, v6
	s_waitcnt lgkmcnt(0)
	v_pk_add_f32 v[6:7], v[6:7], v[10:11]
	ds_bpermute_b32 v11, v102, v7
	ds_bpermute_b32 v10, v102, v6
	s_waitcnt lgkmcnt(0)
	v_pk_add_f32 v[6:7], v[6:7], v[10:11]
	ds_bpermute_b32 v11, v103, v7
	ds_bpermute_b32 v10, v103, v6
	s_waitcnt lgkmcnt(0)
	v_pk_add_f32 v[6:7], v[6:7], v[10:11]
	ds_bpermute_b32 v11, v104, v7
	ds_bpermute_b32 v10, v104, v6
	s_waitcnt lgkmcnt(0)
	v_pk_add_f32 v[6:7], v[6:7], v[10:11]
	ds_bpermute_b32 v11, v105, v7
	ds_bpermute_b32 v10, v105, v6
	s_waitcnt lgkmcnt(0)
	v_pk_add_f32 v[6:7], v[6:7], v[10:11]
	s_nop 0
	v_pk_fma_f32 v[6:7], v[6:7], s[8:9], v[94:95] op_sel_hi:[1,0,0]
	v_add_u32_e32 v95, s2, v95
	v_mul_f32_e32 v10, 0x4b800000, v7
	v_cmp_gt_f32_e32 vcc, s14, v7
	s_nop 1
	v_cndmask_b32_e32 v7, v7, v10, vcc
	v_rsq_f32_e32 v7, v7
	v_lshlrev_b64 v[10:11], 13, v[98:99]
	v_lshl_add_u64 v[10:11], s[24:25], 0, v[10:11]
	v_lshl_add_u64 v[98:99], v[10:11], 0, v[74:75]
	v_mul_f32_e32 v69, 0x45800000, v7
	v_cndmask_b32_e32 v106, v7, v69, vcc
	v_pk_mul_f32 v[60:61], v[60:61], v[106:107] op_sel_hi:[1,0]
	v_pk_mul_f32 v[62:63], v[62:63], v[106:107] op_sel_hi:[1,0]
	v_pk_mul_f32 v[56:57], v[56:57], v[106:107] op_sel_hi:[1,0]
	v_pk_mul_f32 v[58:59], v[58:59], v[106:107] op_sel_hi:[1,0]
	s_waitcnt vmcnt(0)
	v_pk_mul_f32 v[62:63], v[140:141], v[62:63]
	v_pk_mul_f32 v[60:61], v[138:139], v[60:61]
	v_pk_mul_f32 v[58:59], v[136:137], v[58:59]
	v_pk_mul_f32 v[56:57], v[134:135], v[56:57]
	global_store_dwordx4 v[98:99], v[60:63], off
	global_store_dwordx4 v[98:99], v[56:59], off offset:16
	global_load_dwordx4 v[56:59], v[76:77], off offset:2048
	s_nop 0
	global_load_dwordx4 v[60:63], v[76:77], off offset:2064
	v_pk_mul_f32 v[52:53], v[52:53], v[106:107] op_sel_hi:[1,0]
	v_pk_mul_f32 v[48:49], v[48:49], v[106:107] op_sel_hi:[1,0]
	v_pk_mul_f32 v[46:47], v[46:47], v[106:107] op_sel_hi:[1,0]
	v_pk_mul_f32 v[44:45], v[44:45], v[106:107] op_sel_hi:[1,0]
	v_pk_mul_f32 v[38:39], v[38:39], v[106:107] op_sel_hi:[1,0]
	v_pk_mul_f32 v[36:37], v[36:37], v[106:107] op_sel_hi:[1,0]
	v_pk_mul_f32 v[24:25], v[24:25], v[106:107] op_sel_hi:[1,0]
	v_pk_mul_f32 v[28:29], v[28:29], v[106:107] op_sel_hi:[1,0]
	v_mul_f32_e32 v7, 0x4b800000, v6
	v_cmp_gt_f32_e32 vcc, s14, v6
	s_waitcnt vmcnt(1)
	v_pk_mul_f32 v[56:57], v[56:57], v[48:49]
	v_pk_mul_f32 v[58:59], v[58:59], v[52:53]
	s_waitcnt vmcnt(0)
	v_pk_mul_f32 v[44:45], v[60:61], v[44:45]
	v_pk_mul_f32 v[46:47], v[62:63], v[46:47]
	global_store_dwordx4 v[98:99], v[56:59], off offset:2048
	global_store_dwordx4 v[98:99], v[44:47], off offset:2064
	global_load_dwordx4 v[44:47], v[78:79], off
	s_nop 0
	global_load_dwordx4 v[56:59], v[78:79], off offset:16
	v_lshl_add_u64 v[48:49], v[10:11], 0, v[86:87]
	v_pk_mul_f32 v[52:53], v[34:35], v[106:107] op_sel_hi:[1,0]
	v_pk_mul_f32 v[60:61], v[32:33], v[106:107] op_sel_hi:[1,0]
	v_lshl_add_u64 v[10:11], v[10:11], 0, v[88:89]
	v_cndmask_b32_e32 v6, v6, v7, vcc
	s_waitcnt vmcnt(1)
; template <int NR>
; __device__ __forceinline__ void p5_rows(const Params& p, const bf16_t* __restrict__ DL, int r, int nw, int lane) {
;     ...
;         for (int o = 32; o >= 1; o >>= 1) ss += __shfl_xor(ss, o);
;         const float rs = rsqrtf(ss * (1.0f / D) + EPS);
;         float* y = p.out + O_Y + (size_t)row * D;
; #pragma unroll
;         for (int i = 0; i < 4; ++i) { const f32x4 g0 = *(const f32x4*)(p.fng + (i * 64 + lane) * 8), g1 = *(const f32x4*)(p.fng + (i * 64 + lane) * 8 + 4);
;             *(f32x4*)(y + (i * 64 + lane) * 8) = v[k][2 * i] * rs * g0; *(f32x4*)(y + (i * 64 + lane) * 8 + 4) = v[k][2 * i + 1] * rs * g1; } }
; __device__ __forceinline__ void phase5(const Params& p) {
;     ...
;     for (; r + nw < T; r += 2 * nw) p5_rows<2>(p, DL, r, nw, lane);
	v_pk_mul_f32 v[32:33], v[44:45], v[36:37]
	v_pk_mul_f32 v[34:35], v[46:47], v[38:39]
	s_waitcnt vmcnt(0)
	v_pk_mul_f32 v[36:37], v[56:57], v[60:61]
	v_pk_mul_f32 v[38:39], v[58:59], v[52:53]
	global_store_dwordx4 v[48:49], v[32:35], off
	global_store_dwordx4 v[48:49], v[36:39], off offset:16
	global_load_dwordx4 v[32:35], v[80:81], off
	s_nop 0
	global_load_dwordx4 v[36:39], v[80:81], off offset:16
	v_pk_mul_f32 v[44:45], v[22:23], v[106:107] op_sel_hi:[1,0]
	v_pk_mul_f32 v[46:47], v[20:21], v[106:107] op_sel_hi:[1,0]
	s_waitcnt vmcnt(1)
	v_pk_mul_f32 v[20:21], v[28:29], v[32:33]
	v_pk_mul_f32 v[22:23], v[24:25], v[34:35]
	s_waitcnt vmcnt(0)
	v_pk_mul_f32 v[32:33], v[46:47], v[36:37]
	v_pk_mul_f32 v[34:35], v[44:45], v[38:39]
	global_store_dwordx4 v[10:11], v[20:23], off
	global_store_dwordx4 v[10:11], v[32:35], off offset:16
	global_load_dwordx4 v[20:23], v[76:77], off
	s_nop 0
	global_load_dwordx4 v[32:35], v[76:77], off offset:16
	v_rsq_f32_e32 v24, v6
	v_lshl_add_u64 v[6:7], s[24:25], 0, v[96:97]
	v_lshl_add_u64 v[10:11], v[6:7], 0, v[74:75]
	v_mul_f32_e32 v25, 0x45800000, v24
	v_cndmask_b32_e32 v36, v24, v25, vcc
	v_pk_mul_f32 v[24:25], v[30:31], v[36:37] op_sel_hi:[1,0]
	v_pk_mul_f32 v[28:29], v[42:43], v[36:37] op_sel_hi:[1,0]
	v_pk_mul_f32 v[30:31], v[64:65], v[36:37] op_sel_hi:[1,0]
	v_pk_mul_f32 v[38:39], v[66:67], v[36:37] op_sel_hi:[1,0]
	v_pk_mul_f32 v[26:27], v[26:27], v[36:37] op_sel_hi:[1,0]
	v_pk_mul_f32 v[18:19], v[18:19], v[36:37] op_sel_hi:[1,0]
	v_pk_mul_f32 v[4:5], v[4:5], v[36:37] op_sel_hi:[1,0]
	v_pk_mul_f32 v[8:9], v[8:9], v[36:37] op_sel_hi:[1,0]
	s_waitcnt vmcnt(1)
	v_pk_mul_f32 v[20:21], v[20:21], v[28:29]
	v_pk_mul_f32 v[22:23], v[22:23], v[24:25]
	s_waitcnt vmcnt(0)
	v_pk_mul_f32 v[28:29], v[32:33], v[38:39]
	v_pk_mul_f32 v[30:31], v[34:35], v[30:31]
	global_store_dwordx4 v[10:11], v[20:23], off
	global_store_dwordx4 v[10:11], v[28:31], off offset:16
	global_load_dwordx4 v[20:23], v[76:77], off offset:2048
	s_nop 0
	global_load_dwordx4 v[28:31], v[76:77], off offset:2064
	v_pk_mul_f32 v[24:25], v[50:51], v[36:37] op_sel_hi:[1,0]
	v_pk_mul_f32 v[32:33], v[40:41], v[36:37] op_sel_hi:[1,0]
	v_pk_mul_f32 v[34:35], v[54:55], v[36:37] op_sel_hi:[1,0]
	s_waitcnt vmcnt(1)
	v_pk_mul_f32 v[20:21], v[20:21], v[26:27]
	v_pk_mul_f32 v[22:23], v[22:23], v[24:25]
	s_waitcnt vmcnt(0)
	v_pk_mul_f32 v[24:25], v[28:29], v[34:35]
	v_pk_mul_f32 v[26:27], v[30:31], v[32:33]
	global_store_dwordx4 v[10:11], v[20:23], off offset:2048
	global_store_dwordx4 v[10:11], v[24:27], off offset:2064
	global_load_dwordx4 v[20:23], v[78:79], off
	s_nop 0
	global_load_dwordx4 v[24:27], v[78:79], off offset:16
	v_pk_mul_f32 v[10:11], v[16:17], v[36:37] op_sel_hi:[1,0]
	v_lshl_add_u64 v[28:29], v[6:7], 0, v[86:87]
	v_pk_mul_f32 v[16:17], v[14:15], v[36:37] op_sel_hi:[1,0]
	v_pk_mul_f32 v[14:15], v[12:13], v[36:37] op_sel_hi:[1,0]
	s_waitcnt vmcnt(1)
	v_pk_mul_f32 v[10:11], v[20:21], v[10:11]
	v_pk_mul_f32 v[12:13], v[22:23], v[18:19]
	s_waitcnt vmcnt(0)
	v_pk_mul_f32 v[14:15], v[24:25], v[14:15]
	v_pk_mul_f32 v[16:17], v[26:27], v[16:17]
	global_store_dwordx4 v[28:29], v[10:13], off
	global_store_dwordx4 v[28:29], v[14:17], off offset:16
	global_load_dwordx4 v[10:13], v[80:81], off
	s_nop 0
	global_load_dwordx4 v[14:17], v[80:81], off offset:16
	v_lshl_add_u64 v[18:19], v[6:7], 0, v[88:89]
	v_add_u32_e32 v7, s9, v95
	v_cmp_gt_i32_e32 vcc, s74, v7
	v_add_u32_e32 v6, s74, v70
	s_or_b64 s[6:7], vcc, s[6:7]
	v_pk_mul_f32 v[20:21], v[2:3], v[36:37] op_sel_hi:[1,0]
	v_pk_mul_f32 v[22:23], v[0:1], v[36:37] op_sel_hi:[1,0]
	s_waitcnt vmcnt(1)
	v_pk_mul_f32 v[0:1], v[8:9], v[10:11]
	v_pk_mul_f32 v[2:3], v[4:5], v[12:13]
	s_waitcnt vmcnt(0)
	v_pk_mul_f32 v[8:9], v[22:23], v[14:15]
	v_pk_mul_f32 v[10:11], v[20:21], v[16:17]
	global_store_dwordx4 v[18:19], v[0:3], off
	global_store_dwordx4 v[18:19], v[8:11], off offset:16
	s_andn2_b64 exec, exec, s[6:7]
	s_cbranch_execz .LBB0_1197

; __device__ __forceinline__ void phase5(const Params& p) {
;     ...
;     for (; r + nw < T; r += 2 * nw) p5_rows<2>(p, DL, r, nw, lane);
;     if (r < T) p5_rows<1>(p, DL, r, nw, lane);
.LBB0_1197:
	s_or_b64 exec, exec, s[6:7]
	v_add_u32_e32 v70, s9, v95
